# selected-attention key loop: K/V LDS tiles double-buffered, one workgroup barrier per key tile instead of two
# speedup vs baseline: 1.0034x; 1.0034x over previous
; DI int TID() { int t = threadIdx.x; asm volatile("" : "+v"(t)); return t; }
; DI void kv_store(const uint4& k0, const uint4& k1, const uint4& v0, const uint4& v1, u16* sK, u16* sVt) {
;   const int tid = TID(), r0 = tid >> 3, ch = tid & 7;
;   *(uint4*)(sK + r0 * 72 + ch * 8) = k0; *(uint4*)(sK + (r0 + 32) * 72 + ch * 8) = k1;
;   const int ksw = 16 * (ch >> 1);
;   st_kt(sVt, ch * 8, r0 ^ ksw, v0); st_kt(sVt, ch * 8, (r0 + 32) ^ ksw, v1);
; }
; DI void sel_attn_item(const Params& P, int it, u16* sQ, u16* sKunused, u16* sVunused) {
;     ...
;   bf16x8 bq[2][2];
;   int tq[2]; u64 mysel[2];
; #pragma unroll
;   for (int qt = 0; qt < 2; ++qt) {
;     const int rowq = 32 * w + 16 * qt + r16;
;     bq[qt][0] = *(const bf16x8*)(sQ + rowq * 72 + quad * 8);
;     bq[qt][1] = *(const bf16x8*)(sQ + rowq * 72 + 32 + quad * 8);
;     tq[qt] = t0 + 16 * qt + r16;
;     mysel[qt] = SEL[tb + tq[qt]];
;   }
;   u64 uni = 0;
; #pragma unroll
;   for (int q = 0; q < 32; ++q) uni |= SEL[tb + t0 + q];
;   const int cur = t0 >> 6;
;   uni &= (cur == 63) ? ~0ull : ((1ull << (cur + 1)) - 1ull);
;   f32x4 ot[2][4];
; #pragma unroll
;   for (int qt = 0; qt < 2; ++qt)
; #pragma unroll
;     for (int dt = 0; dt < 4; ++dt) ot[qt][dt] = (f32x4){0.f, 0.f, 0.f, 0.f};
;   float m[2] = {-1e30f, -1e30f}, lsum[2] = {0.f, 0.f};
;   uint4 pk0, pk1, pv0, pv1;
;   int kb = uni ? (__ffsll((long long)uni) - 1) : -1;
;   uni &= uni - 1;
;   if (kb >= 0) kv_gload(pk0, pk1, pv0, pv1, PROJ + (tb + kb * 64) * PW + P_KV + 128, PROJ + (tb + kb * 64) * PW + P_KV + 192, PW);
;   for (int nkb = -1; kb >= 0; kb = nkb) {
;     __syncthreads();
;     kv_store(pk0, pk1, pv0, pv1, sK, sVt);
;     __syncthreads();
;     nkb = uni ? (__ffsll((long long)uni) - 1) : -1;
;     uni &= uni - 1;
;     if (nkb >= 0) kv_gload(pk0, pk1, pv0, pv1, PROJ + (tb + nkb * 64) * PW + P_KV + 128, PROJ + (tb + nkb * 64) * PW + P_KV + 192, PW);
.LBB0_242:
	v_and_b32_e32 v8, 15, v169
	v_or_b32_e32 v172, v8, v170
	v_mov_b32_e32 v47, 0
	v_mov_b32_e32 v167, v163
	v_ashrrev_i32_e32 v171, 6, v169
	v_or_b32_e32 v168, 16, v172
	s_andn2_b64 vcc, exec, s[0:1]
	v_mov_b32_e32 v46, v47
	v_mov_b32_e32 v45, v47
	v_mov_b32_e32 v44, v47
	v_mov_b32_e32 v43, v47
	v_mov_b32_e32 v42, v47
	v_mov_b32_e32 v41, v47
	v_mov_b32_e32 v40, v47
	v_mov_b32_e32 v39, v47
	v_mov_b32_e32 v38, v47
	v_mov_b32_e32 v37, v47
	v_mov_b32_e32 v36, v47
	v_mov_b32_e32 v35, v47
	v_mov_b32_e32 v34, v47
	v_mov_b32_e32 v33, v47
	v_mov_b32_e32 v32, v47
	v_mov_b32_e32 v31, v47
	v_mov_b32_e32 v30, v47
	v_mov_b32_e32 v29, v47
	v_mov_b32_e32 v28, v47
	v_mov_b32_e32 v27, v47
	v_mov_b32_e32 v26, v47
	v_mov_b32_e32 v25, v47
	v_mov_b32_e32 v24, v47
	v_mov_b32_e32 v23, v47
	v_mov_b32_e32 v22, v47
	v_mov_b32_e32 v21, v47
	v_mov_b32_e32 v20, v47
	v_mov_b32_e32 v19, v47
	v_mov_b32_e32 v18, v47
	v_mov_b32_e32 v17, v47
	v_mov_b32_e32 v16, v47
	v_mov_b32_e32 v162, v47
	v_mov_b32_e32 v116, v47
	s_cbranch_vccnz .LBB0_219
	v_lshl_or_b32 v6, v171, 5, v8
	v_mul_lo_u32 v6, v6, s6
	v_mov_b32_e32 v173, v163
	v_lshl_add_u32 v6, v7, 4, v6
	v_lshl_add_u64 v[0:1], v[172:173], 3, v[0:1]
	ds_read_b128 v[48:51], v6
	ds_read_b128 v[52:55], v6 offset:64
	ds_read_b128 v[56:59], v6 offset:2304
	ds_read_b128 v[60:63], v6 offset:2368
	global_load_dwordx2 v[174:175], v[0:1], off
	global_load_dwordx2 v[176:177], v[0:1], off offset:128
	v_lshlrev_b32_e32 v0, 6, v9
	v_add_u32_e32 v0, v0, v166
	s_movk_i32 s2, 0x1600
	v_mov_b32_e32 v9, v160
	v_mul_hi_u32 v1, v0, s2
	v_mul_lo_u32 v0, v0, s2
	v_lshl_add_u64 v[0:1], s[54:55], 0, v[0:1]
	v_ashrrev_i32_e32 v10, 3, v9
	v_lshlrev_b32_e32 v9, 4, v9
	v_mad_i64_i32 v[6:7], s[0:1], v10, s2, v[0:1]
	v_and_b32_e32 v162, 0x70, v9
	v_add_u32_e32 v9, 32, v10
	v_lshl_add_u64 v[6:7], v[6:7], 0, v[162:163]
	v_mad_i64_i32 v[0:1], s[0:1], v9, s2, v[0:1]
	v_lshl_add_u64 v[0:1], v[0:1], 0, v[162:163]
	global_load_dwordx4 v[64:67], v[6:7], off offset:768
	global_load_dwordx4 v[68:71], v[6:7], off offset:896
	global_load_dwordx4 v[72:75], v[0:1], off offset:768
	global_load_dwordx4 v[76:79], v[0:1], off offset:896
	v_and_b32_e32 v6, 63, v169
	v_lshl_add_u64 v[0:1], v[2:3], 0, -1
	v_and_b32_e32 v178, v0, v2
	v_and_b32_e32 v179, v1, v3
	v_lshrrev_b32_e32 v0, 1, v169
	v_or_b32_e32 v3, 48, v6
	v_and_b32_e32 v0, 24, v0
	v_mul_u32_u24_e32 v2, 0x48, v8
	v_mul_u32_u24_e32 v3, 0x48, v3
	v_lshlrev_b32_e32 v1, 1, v0
	v_lshlrev_b32_e32 v2, 1, v2
	v_lshlrev_b32_e32 v3, 1, v3
	v_mov_b32_e32 v217, 0
	v_add_u32_e32 v173, v1, v2
	v_add_u32_e32 v210, v1, v3
	v_add_u32_e32 v211, v2, v0
	v_add_u32_e32 v212, v3, v0
	v_mov_b32_e32 v249, v173
	v_mov_b32_e32 v250, v210
	v_mov_b32_e32 v251, v211
	v_mov_b32_e32 v252, v212
	v_mov_b32_e32 v253, 0x4800
	v_sub_u32_e32 v213, 0xff0, v5
	v_add_u32_e32 v214, 14, v172
	v_add_u32_e32 v215, 13, v172
	v_mov_b32_e32 v218, 0xf149f2ca
	v_mov_b32_e32 v221, 0xf149f2ca
	v_mov_b32_e32 v219, 0
	v_mov_b32_e32 v16, 0
	v_mov_b32_e32 v17, v217
	v_mov_b32_e32 v18, v217
	v_mov_b32_e32 v19, v217
	v_mov_b32_e32 v20, 0
	v_mov_b32_e32 v21, v217
	v_mov_b32_e32 v22, v217
	v_mov_b32_e32 v23, v217
	v_mov_b32_e32 v24, 0
	v_mov_b32_e32 v25, v217
	v_mov_b32_e32 v26, v217
	v_mov_b32_e32 v27, v217
	v_mov_b32_e32 v28, 0
	v_mov_b32_e32 v29, v217
	v_mov_b32_e32 v30, v217
	v_mov_b32_e32 v31, v217
	v_mov_b32_e32 v32, 0
	v_mov_b32_e32 v33, v217
	v_mov_b32_e32 v34, v217
	v_mov_b32_e32 v35, v217
	v_mov_b32_e32 v36, 0
	v_mov_b32_e32 v37, v217
	v_mov_b32_e32 v38, v217
	v_mov_b32_e32 v39, v217
	v_mov_b32_e32 v40, 0
	v_mov_b32_e32 v41, v217
	v_mov_b32_e32 v42, v217
	v_mov_b32_e32 v43, v217
	v_mov_b32_e32 v44, 0
	v_mov_b32_e32 v45, v217
	v_mov_b32_e32 v46, v217
	v_mov_b32_e32 v47, v217
.LBB0_244:
	v_mov_b32_e32 v0, v160
	s_waitcnt lgkmcnt(0)
	v_xor_b32_e32 v253, 0x4800, v253
	v_add_u32_e32 v173, v253, v249
	v_add_u32_e32 v210, v253, v250
	v_add_u32_e32 v211, v253, v251
	v_add_u32_e32 v212, v253, v252
	s_movk_i32 s0, 0x90
	v_ashrrev_i32_e32 v1, 3, v0
	v_lshlrev_b32_e32 v0, 3, v0
	v_mul_lo_u32 v2, v1, s0
	v_add_u32_e32 v5, 32, v1
	v_bitop3_b32 v1, v0, v1, 48 bitop3:0x6c
	v_and_b32_e32 v3, 56, v0
	v_lshlrev_b32_e32 v1, 1, v1
	v_bitop3_b32 v0, v5, v0, 48 bitop3:0x78
	v_lshl_add_u32 v2, v3, 1, v2
	v_mad_u32_u24 v1, v3, s0, v1
	v_lshlrev_b32_e32 v0, 1, v0
	v_add_u32_e32 v2, v253, v2
	v_add_u32_e32 v1, v253, v1
	s_waitcnt vmcnt(3)
	ds_write_b128 v2, v[64:67] offset:18432
	s_waitcnt vmcnt(1)
	ds_write_b128 v2, v[72:75] offset:23040
	ds_write_b16 v1, v68 offset:27648
	ds_write_b16_d16_hi v1, v68 offset:27792
	ds_write_b16 v1, v69 offset:27936
	ds_write_b16_d16_hi v1, v69 offset:28080
	ds_write_b16 v1, v70 offset:28224
	ds_write_b16_d16_hi v1, v70 offset:28368
	ds_write_b16 v1, v71 offset:28512
	ds_write_b16_d16_hi v1, v71 offset:28656
	v_mad_u32_u24 v0, v3, s0, v0
	v_add_u32_e32 v0, v253, v0
	v_ffbl_b32_e32 v1, v179
	s_waitcnt vmcnt(0)
	ds_write_b16 v0, v76 offset:27648
	ds_write_b16_d16_hi v0, v76 offset:27792
	ds_write_b16 v0, v77 offset:27936
	ds_write_b16_d16_hi v0, v77 offset:28080
	ds_write_b16 v0, v78 offset:28224
	ds_write_b16_d16_hi v0, v78 offset:28368
	ds_write_b16 v0, v79 offset:28512
	ds_write_b16_d16_hi v0, v79 offset:28656
	v_ffbl_b32_e32 v0, v178
	v_add_u32_e64 v1, v1, 32 clamp
	v_min_u32_e32 v216, v1, v0
	v_cmp_ne_u64_e32 vcc, 0, v[178:179]
	s_waitcnt lgkmcnt(0)
	s_barrier
	v_cndmask_b32_e32 v0, -1, v216, vcc
	v_cmp_gt_i32_e64 s[28:29], 0, v0
	s_and_b64 vcc, exec, s[28:29]
	s_cbranch_vccnz .LBB0_246
	v_lshlrev_b32_e32 v0, 6, v0
	v_add_u32_e32 v0, v0, v166
	s_movk_i32 s2, 0x1600
	v_mov_b32_e32 v5, v160
	v_mul_hi_u32 v1, v0, s2
	v_mul_lo_u32 v0, v0, s2
	v_lshl_add_u64 v[0:1], s[54:55], 0, v[0:1]
	v_ashrrev_i32_e32 v6, 3, v5
	v_lshlrev_b32_e32 v5, 4, v5
	v_mad_i64_i32 v[2:3], s[0:1], v6, s2, v[0:1]
	v_and_b32_e32 v162, 0x70, v5
	v_add_u32_e32 v5, 32, v6
	v_lshl_add_u64 v[2:3], v[2:3], 0, v[162:163]
	v_mad_i64_i32 v[0:1], s[0:1], v5, s2, v[0:1]
	v_lshl_add_u64 v[0:1], v[0:1], 0, v[162:163]
	global_load_dwordx4 v[64:67], v[2:3], off offset:768
	global_load_dwordx4 v[68:71], v[2:3], off offset:896
	global_load_dwordx4 v[72:75], v[0:1], off offset:768
	global_load_dwordx4 v[76:79], v[0:1], off offset:896
